# radix3 on p11pos+sel_ip: radix-select bit as a mask (2-instr loop control) + half-width variant for qblk < 64
# baseline (speedup 1.0000x reference)
.LBB0_1029:
	s_or_b64 exec, exec, s[0:1]
	s_waitcnt lgkmcnt(0)
	s_barrier
	ds_read2st64_b32 v[0:1], v173 offset1:1
	v_add_u32_e32 v7, 0xf0, v174
	ds_read_b64 v[2:3], v161
	ds_read_b64 v[8:9], v162
	ds_read_b64 v[10:11], v163
	ds_read_b64 v[12:13], v164
	ds_read2st64_b32 v[14:15], v174 offset1:1
	ds_read2st64_b32 v[16:17], v174 offset0:33 offset1:34
	ds_read2st64_b32 v[18:19], v174 offset0:66 offset1:67
	ds_read2st64_b32 v[20:21], v174 offset0:99 offset1:100
	ds_read2st64_b32 v[22:23], v7 offset0:30 offset1:31
	ds_read2st64_b32 v[24:25], v7 offset0:63 offset1:64
	ds_read2st64_b32 v[26:27], v7 offset0:96 offset1:97
	ds_read2st64_b32 v[28:29], v7 offset0:129 offset1:130
	ds_read_b64 v[30:31], v165
	ds_read_b64 v[32:33], v166
	ds_read_b64 v[34:35], v167
	ds_read_b64 v[36:37], v168
	ds_read2st64_b32 v[38:39], v7 offset0:162 offset1:163
	ds_read2st64_b32 v[40:41], v7 offset0:195 offset1:196
	ds_read2st64_b32 v[42:43], v7 offset0:228 offset1:229
	ds_read2st64_b32 v[44:45], v174 offset0:132 offset1:133
	ds_read2st64_b32 v[46:47], v174 offset0:165 offset1:166
	ds_read2st64_b32 v[80:81], v174 offset0:198 offset1:199
	ds_read2st64_b32 v[82:83], v174 offset0:231 offset1:232
	s_ashr_i32 s30, s75, 2
	s_add_i32 s31, s30, -1
	s_max_i32 s31, s31, 0
	s_lshl_b32 s98, s40, 25
	s_add_u32 s98, s36, s98
	s_addc_u32 s99, s37, 0
	s_lshl_b32 s20, s29, 7
	s_add_u32 s98, s98, s20
	s_addc_u32 s99, s99, 0
	s_lshl_b32 s20, s47, 20
	s_add_u32 s100, s55, s20
	s_addc_u32 s101, s56, 0
	v_mov_b32_e32 v198, v138
	v_mov_b32_e32 v199, 0
	v_mov_b32_e32 v200, v140
	v_mov_b32_e32 v201, 0
	s_lshl_b32 s22, s30, 18
	s_add_u32 s22, s98, s22
	s_addc_u32 s23, s99, 0
	s_lshl_b32 s24, s30, 7
	s_add_u32 s24, s100, s24
	s_addc_u32 s25, s101, 0
	v_lshl_add_u64 v[194:195], s[22:23], 0, v[198:199]
	v_lshl_add_u64 v[196:197], s[24:25], 0, v[200:201]
	v_lshl_add_u64 v[194:195], v[194:195], 0, v[122:123]
	v_lshl_add_u64 v[196:197], v[196:197], 0, v[122:123]
	global_load_dwordx4 v[240:243], v[194:195], off offset:2560
	global_load_dwordx4 v[244:247], v[196:197], off
	s_lshl_b32 s22, s31, 18
	s_add_u32 s22, s98, s22
	s_addc_u32 s23, s99, 0
	s_lshl_b32 s24, s31, 7
	s_add_u32 s24, s100, s24
	s_addc_u32 s25, s101, 0
	v_lshl_add_u64 v[194:195], s[22:23], 0, v[198:199]
	v_lshl_add_u64 v[196:197], s[24:25], 0, v[200:201]
	v_lshl_add_u64 v[194:195], v[194:195], 0, v[122:123]
	v_lshl_add_u64 v[196:197], v[196:197], 0, v[122:123]
	global_load_dwordx4 v[248:251], v[194:195], off offset:2560
	global_load_dwordx4 v[252:255], v[196:197], off
	s_ashr_i32 s76, s75, 2
	v_cmp_eq_u32_e64 s[0:1], s76, v128
	s_waitcnt lgkmcnt(14)
	v_mov_b32_e32 v84, v1
	v_mov_b32_e32 v85, v0
	v_pk_fma_f32 v[0:1], v[2:3], v[84:85], 0 op_sel_hi:[0,1,0]
	v_mov_b32_e32 v84, v23
	v_mov_b32_e32 v85, v22
	v_pk_fma_f32 v[0:1], v[8:9], v[84:85], v[0:1] op_sel_hi:[0,1,1]
	s_waitcnt lgkmcnt(13)
	v_mov_b32_e32 v22, v25
	v_mov_b32_e32 v23, v24
	v_pk_fma_f32 v[0:1], v[10:11], v[22:23], v[0:1] op_sel_hi:[0,1,1]
	s_waitcnt lgkmcnt(12)
	v_mov_b32_e32 v22, v27
	v_mov_b32_e32 v23, v26
	v_pk_fma_f32 v[0:1], v[12:13], v[22:23], v[0:1] op_sel_hi:[0,1,1]
	s_waitcnt lgkmcnt(11)
	v_mov_b32_e32 v22, v29
	v_mov_b32_e32 v23, v28
	s_waitcnt lgkmcnt(10)
	v_pk_fma_f32 v[0:1], v[30:31], v[22:23], v[0:1] op_sel_hi:[0,1,1]
	s_waitcnt lgkmcnt(6)
	v_mov_b32_e32 v22, v39
	v_mov_b32_e32 v23, v38
	v_pk_fma_f32 v[0:1], v[32:33], v[22:23], v[0:1] op_sel_hi:[0,1,1]
	s_waitcnt lgkmcnt(5)
	v_mov_b32_e32 v22, v41
	v_mov_b32_e32 v23, v40
	v_pk_fma_f32 v[0:1], v[34:35], v[22:23], v[0:1] op_sel_hi:[0,1,1]
	s_waitcnt lgkmcnt(4)
	v_mov_b32_e32 v22, v43
	v_mov_b32_e32 v23, v42
	v_pk_fma_f32 v[0:1], v[36:37], v[22:23], v[0:1] op_sel_hi:[0,1,1]
	v_mov_b32_e32 v22, v15
	v_mov_b32_e32 v23, v14
	v_pk_fma_f32 v[2:3], v[2:3], v[22:23], 0 op_sel:[1,0,0] op_sel_hi:[1,1,0]
	v_mov_b32_e32 v14, v17
	v_mov_b32_e32 v15, v16
	v_pk_fma_f32 v[2:3], v[8:9], v[14:15], v[2:3] op_sel:[1,0,0]
	v_mov_b32_e32 v8, v19
	v_mov_b32_e32 v9, v18
	v_pk_fma_f32 v[2:3], v[10:11], v[8:9], v[2:3] op_sel:[1,0,0]
	v_mov_b32_e32 v8, v21
	v_mov_b32_e32 v9, v20
	v_pk_fma_f32 v[2:3], v[12:13], v[8:9], v[2:3] op_sel:[1,0,0]
	s_waitcnt lgkmcnt(3)
	v_mov_b32_e32 v8, v45
	v_mov_b32_e32 v9, v44
	v_pk_fma_f32 v[2:3], v[30:31], v[8:9], v[2:3] op_sel:[1,0,0]
	s_waitcnt lgkmcnt(2)
	v_mov_b32_e32 v8, v47
	v_mov_b32_e32 v9, v46
	s_add_i32 s24, s76, 0xffffffbf
	s_add_i32 s22, s76, -1
	v_pk_fma_f32 v[2:3], v[32:33], v[8:9], v[2:3] op_sel:[1,0,0]
	s_waitcnt lgkmcnt(1)
	v_mov_b32_e32 v8, v81
	v_mov_b32_e32 v9, v80
	s_or_b64 s[26:27], s[6:7], s[0:1]
	v_cmp_eq_u32_e64 s[0:1], s76, v156
	v_pk_fma_f32 v[2:3], v[34:35], v[8:9], v[2:3] op_sel:[1,0,0]
	s_waitcnt lgkmcnt(0)
	v_mov_b32_e32 v8, v83
	v_mov_b32_e32 v9, v82
	v_cmp_eq_u32_e64 s[22:23], s22, v127
	v_cmp_eq_u32_e64 s[24:25], s24, v128
	v_pk_fma_f32 v[8:9], v[36:37], v[8:9], v[2:3] op_sel:[1,0,0]
	s_or_b64 s[22:23], s[26:27], s[22:23]
	s_or_b64 s[0:1], s[0:1], s[24:25]
	v_cmp_ge_i32_e64 s[20:21], s76, v128
	v_cmp_ge_i32_e32 vcc, s76, v156
	v_cndmask_b32_e64 v3, v1, v182, s[22:23]
	v_cndmask_b32_e64 v2, v0, v182, s[0:1]
	v_cndmask_b32_e64 v1, v9, v182, s[22:23]
	v_cndmask_b32_e64 v0, v8, v182, s[0:1]
	s_mov_b32 s77, 30
	s_mov_b32 s31, 0
	s_mov_b32 s30, 0
	s_mov_b32 s98, 64
	s_mov_b32 s100, 64
	s_cmp_lt_i32 s76, 16
	s_cbranch_scc1 .Lradix_done
	v_cndmask_b32_e64 v8, 0, v3, s[20:21]
	v_cndmask_b32_e32 v9, 0, v2, vcc
	v_cndmask_b32_e64 v10, 0, v1, s[20:21]
	v_cndmask_b32_e32 v11, 0, v0, vcc
	s_mov_b32 s77, 0x40000000
	s_cmp_lt_i32 s76, 64
	s_cbranch_scc1 .Lradix_lo
.LBB0_1030:
	s_or_b32 s78, s77, s31
	s_or_b32 s79, s77, s30
	v_cmp_le_u32_e64 s[0:1], s78, v8
	v_cmp_le_u32_e64 s[22:23], s78, v9
	v_cmp_le_u32_e64 s[24:25], s79, v10
	v_cmp_le_u32_e64 s[26:27], s79, v11
	s_bcnt1_i32_b64 s0, s[0:1]
	s_bcnt1_i32_b64 s1, s[22:23]
	s_bcnt1_i32_b64 s22, s[24:25]
	s_bcnt1_i32_b64 s23, s[26:27]
	s_add_i32 s1, s1, s0
	s_add_i32 s23, s23, s22
	s_cmp_gt_u32 s1, 15
	s_cselect_b32 s31, s78, s31
	s_cselect_b32 s98, s1, s98
	s_cmp_gt_u32 s23, 15
	s_cselect_b32 s30, s79, s30
	s_cselect_b32 s100, s23, s100
	s_add_i32 s0, s98, s100
	s_cmp_eq_u32 s0, 32
	s_cbranch_scc1 .Lradix_done
	s_lshr_b32 s77, s77, 1
	s_cbranch_scc1 .LBB0_1030
	s_branch .Lradix_done
.Lradix_lo:
	s_or_b32 s78, s77, s31
	s_or_b32 s79, s77, s30
	v_cmp_le_u32_e64 s[0:1], s78, v8
	v_cmp_le_u32_e64 s[24:25], s79, v10
	s_bcnt1_i32_b64 s1, s[0:1]
	s_bcnt1_i32_b64 s23, s[24:25]
	s_cmp_gt_u32 s1, 15
	s_cselect_b32 s31, s78, s31
	s_cselect_b32 s98, s1, s98
	s_cmp_gt_u32 s23, 15
	s_cselect_b32 s30, s79, s30
	s_cselect_b32 s100, s23, s100
	s_add_i32 s0, s98, s100
	s_cmp_eq_u32 s0, 32
	s_cbranch_scc1 .Lradix_done
	s_lshr_b32 s77, s77, 1
	s_cbranch_scc1 .Lradix_lo
